# prompt diff_item epilogue: group A issues its 16 gate loads before the loop-end vmcnt drain and barrier (counted vmcnt(16)), B waves unchanged
# baseline (speedup 1.0000x reference)
; DI void diff_core(unsigned char* smem, const u16* qptr, const u16* kbase, const u16* vtbase, int vld,
;                   int ntb, int ntw, int nvalid, int ks0, const float* lut, int qpos, bool active, bool grpB,
;                   f32x16 (&O)[4], float& l_out) {
;     ...
;   __builtin_amdgcn_s_setprio(0);
;   asm volatile("s_waitcnt vmcnt(0)" ::: "memory");
;   __syncthreads();
; __device__ void diff_item(const Params& p, unsigned char* smem, bool sample, int b, int h, int qb, float lam) {
;     ...
;   if (c == 0 && active) {
;     const u16* grow = p.Gb + (size_t)tok * 2048 + h * 128;
; #pragma unroll
;     for (int t = 0; t < 4; ++t)
; #pragma unroll
;       for (int gq = 0; gq < 4; ++gq) gv[t * 4 + gq] = *reinterpret_cast<const u32x2*>(grow + 32 * t + 8 * gq + 4 * hh);
;   }
;   float* ex = reinterpret_cast<float*>(smem) + g * 4096;
;   if (c == 1 && active) {
;     const float sc = lam / l;
; #pragma unroll
;     for (int t = 0; t < 4; ++t)
; #pragma unroll
;       for (int i = 0; i < 16; ++i) ex[(t * 16 + i) * 64 + lane] = O[t][i] * sc;
.LBB0_388:
	s_nop 3
	v_and_b32_e32 v88, 63, v175
	s_lshl_b32 s14, s57, 7
	s_setprio 0
	v_and_b32_e32 v65, 64, v161
	v_xor_b32_e32 v64, 32, v161
	v_add_u32_e32 v65, 64, v65
	v_cmp_lt_i32_e32 vcc, v64, v65
	s_cmpk_lt_u32 s56, 0x100
	s_cselect_b64 s[0:1], -1, 0
	v_cndmask_b32_e32 v64, v161, v64, vcc
	v_lshlrev_b32_e32 v99, 2, v64
	ds_bpermute_b32 v89, v99, v181
	v_lshlrev_b32_e32 v162, 3, v174
	s_cmpk_gt_u32 s56, 0xff
	s_cbranch_scc1 .Lg_B
	v_lshl_add_u64 v[252:253], v[164:165], 1, s[80:81]
	s_lshl_b32 s6, s14, 1
	v_lshl_add_u64 v[252:253], v[252:253], 0, s[6:7]
	v_lshl_add_u64 v[252:253], v[252:253], 0, v[162:163]
	global_load_dwordx2 v[96:97], v[252:253], off
	global_load_dwordx2 v[94:95], v[252:253], off offset:16
	global_load_dwordx2 v[92:93], v[252:253], off offset:32
	global_load_dwordx2 v[90:91], v[252:253], off offset:48
	global_load_dwordx2 v[86:87], v[252:253], off offset:64
	global_load_dwordx2 v[84:85], v[252:253], off offset:80
	global_load_dwordx2 v[82:83], v[252:253], off offset:96
	global_load_dwordx2 v[80:81], v[252:253], off offset:112
	global_load_dwordx2 v[78:79], v[252:253], off offset:128
	global_load_dwordx2 v[76:77], v[252:253], off offset:144
	global_load_dwordx2 v[74:75], v[252:253], off offset:160
	global_load_dwordx2 v[72:73], v[252:253], off offset:176
	global_load_dwordx2 v[70:71], v[252:253], off offset:192
	global_load_dwordx2 v[68:69], v[252:253], off offset:208
	global_load_dwordx2 v[66:67], v[252:253], off offset:224
	global_load_dwordx2 v[64:65], v[252:253], off offset:240
	s_waitcnt vmcnt(16) lgkmcnt(0)
	s_branch .Lg_join
.Lg_B:
	s_waitcnt vmcnt(0) lgkmcnt(0)
.Lg_join:
	s_barrier
.LBB0_390:
	s_lshl_b32 s6, s39, 14
	s_add_i32 s6, s6, 0
	v_add_f32_e32 v89, v181, v89
	s_andn2_b64 vcc, exec, s[12:13]
	v_lshl_add_u32 v88, v88, 2, s6
	s_cbranch_vccnz .LBB0_392
	v_div_scale_f32 v98, s[12:13], v89, v89, v193
	v_rcp_f32_e32 v100, v98
	v_div_scale_f32 v101, vcc, v193, v89, v193
	v_fma_f32 v102, -v98, v100, 1.0
	v_fmac_f32_e32 v100, v102, v100
	v_mul_f32_e32 v102, v101, v100
	v_fma_f32 v103, -v98, v102, v101
	v_fmac_f32_e32 v102, v103, v100
	v_fma_f32 v98, -v98, v102, v101
	v_div_fmas_f32 v98, v98, v100, v102
	v_div_fixup_f32 v98, v98, v89, v193
	v_mul_f32_e32 v100, v48, v98
	v_mul_f32_e32 v101, v49, v98
	ds_write2st64_b32 v88, v100, v101 offset1:1
	v_mul_f32_e32 v100, v50, v98
	v_mul_f32_e32 v101, v51, v98
	ds_write2st64_b32 v88, v100, v101 offset0:2 offset1:3
	v_mul_f32_e32 v100, v52, v98
	v_mul_f32_e32 v101, v53, v98
	ds_write2st64_b32 v88, v100, v101 offset0:4 offset1:5
	v_mul_f32_e32 v100, v54, v98
	v_mul_f32_e32 v101, v55, v98
	ds_write2st64_b32 v88, v100, v101 offset0:6 offset1:7
	v_mul_f32_e32 v100, v56, v98
	v_mul_f32_e32 v101, v57, v98
	ds_write2st64_b32 v88, v100, v101 offset0:8 offset1:9
	v_mul_f32_e32 v100, v58, v98
	v_mul_f32_e32 v101, v59, v98
	ds_write2st64_b32 v88, v100, v101 offset0:10 offset1:11
	v_mul_f32_e32 v100, v60, v98
	v_mul_f32_e32 v101, v61, v98
	ds_write2st64_b32 v88, v100, v101 offset0:12 offset1:13
	v_mul_f32_e32 v100, v62, v98
	v_mul_f32_e32 v101, v63, v98
	ds_write2st64_b32 v88, v100, v101 offset0:14 offset1:15
	v_mul_f32_e32 v100, v32, v98
	v_mul_f32_e32 v101, v33, v98
	ds_write2st64_b32 v88, v100, v101 offset0:16 offset1:17
	v_mul_f32_e32 v100, v34, v98
	v_mul_f32_e32 v101, v35, v98
	ds_write2st64_b32 v88, v100, v101 offset0:18 offset1:19
	v_mul_f32_e32 v100, v36, v98
	v_mul_f32_e32 v101, v37, v98
	ds_write2st64_b32 v88, v100, v101 offset0:20 offset1:21
	v_mul_f32_e32 v100, v38, v98
	v_mul_f32_e32 v101, v39, v98
	ds_write2st64_b32 v88, v100, v101 offset0:22 offset1:23
	v_mul_f32_e32 v100, v40, v98
	v_mul_f32_e32 v101, v41, v98
	ds_write2st64_b32 v88, v100, v101 offset0:24 offset1:25
	v_mul_f32_e32 v100, v42, v98
	v_mul_f32_e32 v101, v43, v98
	ds_write2st64_b32 v88, v100, v101 offset0:26 offset1:27
	v_mul_f32_e32 v100, v44, v98
	v_mul_f32_e32 v101, v45, v98
	ds_write2st64_b32 v88, v100, v101 offset0:28 offset1:29
	v_mul_f32_e32 v100, v46, v98
	v_mul_f32_e32 v101, v47, v98
	ds_write2st64_b32 v88, v100, v101 offset0:30 offset1:31
	v_mul_f32_e32 v100, v16, v98
	v_mul_f32_e32 v101, v17, v98
	ds_write2st64_b32 v88, v100, v101 offset0:32 offset1:33
	v_mul_f32_e32 v100, v18, v98
	v_mul_f32_e32 v101, v19, v98
	ds_write2st64_b32 v88, v100, v101 offset0:34 offset1:35
	v_mul_f32_e32 v100, v20, v98
	v_mul_f32_e32 v101, v21, v98
	ds_write2st64_b32 v88, v100, v101 offset0:36 offset1:37
	v_mul_f32_e32 v100, v22, v98
	v_mul_f32_e32 v101, v23, v98
	ds_write2st64_b32 v88, v100, v101 offset0:38 offset1:39
	v_mul_f32_e32 v100, v24, v98
	v_mul_f32_e32 v101, v25, v98
	ds_write2st64_b32 v88, v100, v101 offset0:40 offset1:41
	v_mul_f32_e32 v100, v26, v98
	v_mul_f32_e32 v101, v27, v98
	ds_write2st64_b32 v88, v100, v101 offset0:42 offset1:43
	v_mul_f32_e32 v100, v28, v98
	v_mul_f32_e32 v101, v29, v98
	ds_write2st64_b32 v88, v100, v101 offset0:44 offset1:45
	v_mul_f32_e32 v100, v30, v98
	v_mul_f32_e32 v101, v31, v98
	ds_write2st64_b32 v88, v100, v101 offset0:46 offset1:47
	v_mul_f32_e32 v100, v0, v98
	v_mul_f32_e32 v101, v1, v98
	ds_write2st64_b32 v88, v100, v101 offset0:48 offset1:49
	v_mul_f32_e32 v100, v2, v98
	v_mul_f32_e32 v101, v3, v98
	ds_write2st64_b32 v88, v100, v101 offset0:50 offset1:51
	v_mul_f32_e32 v100, v4, v98
	v_mul_f32_e32 v101, v5, v98
	ds_write2st64_b32 v88, v100, v101 offset0:52 offset1:53
	v_mul_f32_e32 v100, v6, v98
	v_mul_f32_e32 v101, v7, v98
	ds_write2st64_b32 v88, v100, v101 offset0:54 offset1:55
	v_mul_f32_e32 v100, v8, v98
	v_mul_f32_e32 v101, v9, v98
	ds_write2st64_b32 v88, v100, v101 offset0:56 offset1:57
	v_mul_f32_e32 v100, v10, v98
	v_mul_f32_e32 v101, v11, v98
	ds_write2st64_b32 v88, v100, v101 offset0:58 offset1:59
	v_mul_f32_e32 v100, v12, v98
	v_mul_f32_e32 v101, v13, v98
	ds_write2st64_b32 v88, v100, v101 offset0:60 offset1:61
	v_mul_f32_e32 v100, v14, v98
	v_mul_f32_e32 v98, v15, v98
	ds_write2st64_b32 v88, v100, v98 offset0:62 offset1:63
